# one-pass LRU: tile order 4 batches x 4 consecutive chunks per iteration, look-back over 3 chunks instead of 15
# speedup vs baseline: 1.0035x; 1.0035x over previous
; template <int PASS> __device__ void lru_phase(const Params& p, unsigned char* smem) {
;     ...
;     if ((int)blockIdx.x < 4096) LRU_CLOAD((int)blockIdx.x);
.LBB0_527:
	v_readlane_b32 s4, v251, 32
	v_readlane_b32 s5, v251, 33
	s_load_dwordx4 s[64:67], s[4:5], 0x150
	s_waitcnt lgkmcnt(0)
	s_load_dword s62, s[4:5], 0x160
	v_readlane_b32 s70, v251, 42
	v_readfirstlane_b32 s6, v1
	s_add_u32 s0, s64, 0x4000000
	s_addc_u32 s1, s65, 0
	s_cmpk_lt_i32 s70, 0x1000
	s_cselect_b64 s[2:3], -1, 0
	s_cmpk_gt_i32 s70, 0xfff
	s_cbranch_scc1 .LBB0_537
	s_lshl_b32 s4, s70, 7
	s_waitcnt vmcnt(0)
	v_lshlrev_b32_e32 v3, 3, v1
	s_and_b32 s4, s4, 0x780
	v_and_b32_e32 v3, 0x78, v3
	v_or_b32_e32 v3, s4, v3
	s_and_b32 s63, s70, 0x3f
	s_lshr_b32 s71, s70, 8
	s_lshl_b32 s71, s71, 6
	s_or_b32 s63, s63, s71
	s_bfe_u32 s71, s70, 0x20006
	s_lshl_b32 s71, s71, 10
	s_or_b32 s63, s63, s71
	s_lshl_b32 s4, s63, 2
	v_lshrrev_b32_e32 v2, 4, v1
	s_and_b32 s5, s4, 0xfc0
	v_or_b32_e32 v14, s5, v2
	v_lshlrev_b32_e32 v2, 1, v3
	v_mov_b32_e32 v3, 0
	v_mov_b32_e32 v4, v3
	v_mov_b32_e32 v5, v3
	v_add_u32_e32 v15, -3, v14
	v_lshl_add_u64 v[30:31], s[0:1], 0, v[2:3]
	v_mov_b32_e32 v2, v3
	v_mov_b64_e32 v[8:9], v[4:5]
	s_and_b32 s7, s4, 0xfffff000
	v_cmp_lt_i32_e32 vcc, -1, v15
	v_mov_b64_e32 v[6:7], v[2:3]
	s_and_saveexec_b64 s[4:5], vcc
	s_cbranch_execz .LBB0_530
	v_add_u32_e32 v6, s7, v15
	v_ashrrev_i32_e32 v7, 31, v6
	v_lshlrev_b64 v[6:7], 12, v[6:7]
	v_lshl_add_u64 v[6:7], v[30:31], 0, v[6:7]
	global_load_dwordx4 v[6:9], v[6:7], off

; __device__ __forceinline__ void unpack8(u32x4 w, float* f) { f[0] = bflo(w.x); f[1] = bfhi(w.x); f[2] = bflo(w.y); f[3] = bfhi(w.y); f[4] = bflo(w.z); f[5] = bfhi(w.z); f[6] = bflo(w.w); f[7] = bfhi(w.w); }
; template <int PASS> __device__ void lru_phase(const Params& p, unsigned char* smem) {
;     ...
;     for (int tile = blockIdx.x; tile < 4096; tile += gridDim.x) {
;         const int jb = tile & 15, c = (tile >> 4) & 63, b = tile >> 10;
;         const int row0 = b * SEQL + c * 64;
;         u16 zpre[16];
;         if (PASS == 2) {
; #pragma unroll
;             for (int tt = 0; tt < 16; ++tt) zpre[tt] = Y0[(size_t)(row0 + (tid >> 7) * 16 + tt) * 4096 + jb * 128 + (tid & 127)];
;         }
; #pragma unroll
;         for (int it = 0; it < 2; ++it) {
;             const int t = (tid >> 4) + 32 * it, c8 = (tid & 15) * 8, ch = jb * 128 + c8;
;             float acc[8];
;             { const f32x4 b0 = *(const f32x4*)(cb + ch), b1 = *(const f32x4*)(cb + ch + 4);
; #pragma unroll
;               for (int i = 0; i < 4; ++i) { acc[i] = b0[i]; acc[4 + i] = b1[i]; } }
; #pragma unroll
;             for (int j = 0; j < 4; ++j) { float xv[8]; unpack8(craw[it][j], xv);
;                 const f32x4 w0 = *(const f32x4*)(cw + j * 2048 + ch), w1 = *(const f32x4*)(cw + j * 2048 + ch + 4);
LRUW2_staged:
	s_and_b32 s63, s37, 0x3f
	s_lshr_b32 s71, s37, 8
	s_lshl_b32 s71, s71, 6
	s_or_b32 s63, s63, s71
	s_bfe_u32 s71, s37, 0x20006
	s_lshl_b32 s71, s71, 10
	s_or_b32 s63, s63, s71
	s_bfe_u32 s24, s63, 0x60004
	s_ashr_i32 s25, s63, 10
	s_lshl_b32 s4, s25, 12
	s_lshl_b32 s5, s24, 6
	s_or_b32 s38, s5, s4
	s_and_b32 s40, s37, 15
	v_add_u32_e32 v108, s38, v131
	s_lshl_b32 s12, s40, 8
	v_ashrrev_i32_e32 v109, 31, v108
	v_lshl_add_u64 v[110:111], v[124:125], 0, s[12:13]
	v_lshlrev_b64 v[68:69], 13, v[108:109]
	v_lshl_add_u64 v[112:113], v[110:111], 0, v[68:69]
	v_or_b32_e32 v68, 1, v108
	v_ashrrev_i32_e32 v69, 31, v68
	v_lshlrev_b64 v[68:69], 13, v[68:69]
	v_lshl_add_u64 v[114:115], v[110:111], 0, v[68:69]
	v_or_b32_e32 v68, 2, v108
	v_ashrrev_i32_e32 v69, 31, v68
	s_lshl_b32 s39, s40, 7
	v_lshlrev_b64 v[68:69], 13, v[68:69]
	v_readlane_b32 s44, v251, 0
	v_lshl_add_u64 v[116:117], v[110:111], 0, v[68:69]
	v_or_b32_e32 v68, 3, v108
	v_or_b32_e32 v66, s39, v134
	v_readlane_b32 s46, v251, 2
	v_readlane_b32 s47, v251, 3
	v_ashrrev_i32_e32 v69, 31, v68
	v_lshlrev_b32_e32 v66, 2, v66
	s_mov_b64 s[42:43], s[46:47]
	v_lshlrev_b64 v[68:69], 13, v[68:69]
	v_lshl_add_u64 v[104:105], s[42:43], 0, v[66:67]
	v_lshl_add_u64 v[118:119], v[110:111], 0, v[68:69]
	v_or_b32_e32 v68, 4, v108
	v_add_co_u32_e32 v76, vcc, s28, v104
	v_ashrrev_i32_e32 v69, 31, v68
	s_nop 0
	v_addc_co_u32_e32 v77, vcc, 0, v105, vcc
	v_lshlrev_b64 v[68:69], 13, v[68:69]
	v_readlane_b32 s48, v251, 4
	v_readlane_b32 s49, v251, 5
	v_add_co_u32_e32 v80, vcc, s29, v104
	v_lshl_add_u64 v[120:121], v[110:111], 0, v[68:69]
	s_nop 2
	ds_read_b128 v[68:71], v249 offset:2048
	ds_read_b128 v[72:75], v249
	v_addc_co_u32_e32 v81, vcc, 0, v105, vcc
	ds_read_b128 v[76:79], v249 offset:512
	v_add_co_u32_e32 v84, vcc, s30, v104
	ds_read_b128 v[80:83], v249 offset:1024
	s_nop 0
	v_addc_co_u32_e32 v85, vcc, 0, v105, vcc
	ds_read_b128 v[84:87], v249 offset:1536
	v_or_b32_e32 v100, 5, v108
	ds_read_b128 v[88:91], v249 offset:2064
	ds_read_b128 v[92:95], v249 offset:16
	v_ashrrev_i32_e32 v101, 31, v100
	v_lshl_add_u64 v[96:97], v[104:105], 0, s[16:17]
	ds_read_b128 v[96:99], v249 offset:528
	v_lshlrev_b64 v[106:107], 13, v[100:101]
	v_lshl_add_u64 v[100:101], v[104:105], 0, s[18:19]
	ds_read_b128 v[100:103], v249 offset:1040
	v_lshl_add_u64 v[104:105], v[104:105], 0, s[20:21]
	v_lshl_add_u64 v[122:123], v[110:111], 0, v[106:107]
	ds_read_b128 v[104:107], v249 offset:1552
	v_or_b32_e32 v212, 6, v108
	v_ashrrev_i32_e32 v213, 31, v212
	v_or_b32_e32 v214, 7, v108
	v_lshlrev_b64 v[212:213], 13, v[212:213]
	v_ashrrev_i32_e32 v215, 31, v214
	v_lshl_add_u64 v[212:213], v[110:111], 0, v[212:213]
	v_lshlrev_b64 v[214:215], 13, v[214:215]
	v_lshl_add_u64 v[214:215], v[110:111], 0, v[214:215]
	global_load_ushort v227, v[112:113], off
	global_load_ushort v226, v[114:115], off
	global_load_ushort v225, v[116:117], off
	global_load_ushort v224, v[118:119], off
	global_load_ushort v223, v[120:121], off
	global_load_ushort v222, v[122:123], off
	global_load_ushort v221, v[212:213], off
	global_load_ushort v219, v[214:215], off
	v_or_b32_e32 v112, 8, v108
	v_or_b32_e32 v212, 14, v108
	v_ashrrev_i32_e32 v113, 31, v112
	v_or_b32_e32 v114, 9, v108
	v_or_b32_e32 v116, 10, v108
	v_or_b32_e32 v118, 11, v108
	v_or_b32_e32 v120, 12, v108
	v_or_b32_e32 v122, 13, v108
	v_ashrrev_i32_e32 v213, 31, v212
	v_or_b32_e32 v108, 15, v108
	v_lshlrev_b64 v[112:113], 13, v[112:113]
	v_ashrrev_i32_e32 v115, 31, v114
	v_ashrrev_i32_e32 v117, 31, v116
	v_ashrrev_i32_e32 v119, 31, v118
	v_ashrrev_i32_e32 v121, 31, v120
	v_ashrrev_i32_e32 v123, 31, v122
	v_lshlrev_b64 v[212:213], 13, v[212:213]
	v_ashrrev_i32_e32 v109, 31, v108
	v_lshl_add_u64 v[112:113], v[110:111], 0, v[112:113]
	v_lshlrev_b64 v[114:115], 13, v[114:115]
	v_lshlrev_b64 v[116:117], 13, v[116:117]
	v_lshlrev_b64 v[118:119], 13, v[118:119]
	v_lshlrev_b64 v[120:121], 13, v[120:121]
	v_lshlrev_b64 v[122:123], 13, v[122:123]
	v_lshl_add_u64 v[212:213], v[110:111], 0, v[212:213]
	v_lshlrev_b64 v[108:109], 13, v[108:109]
	v_lshl_add_u64 v[114:115], v[110:111], 0, v[114:115]
	v_lshl_add_u64 v[116:117], v[110:111], 0, v[116:117]
	v_lshl_add_u64 v[118:119], v[110:111], 0, v[118:119]
	v_lshl_add_u64 v[120:121], v[110:111], 0, v[120:121]
	v_lshl_add_u64 v[122:123], v[110:111], 0, v[122:123]
	v_lshl_add_u64 v[108:109], v[110:111], 0, v[108:109]
	global_load_ushort v220, v[112:113], off
	global_load_ushort v218, v[114:115], off
	global_load_ushort v217, v[116:117], off
	global_load_ushort v216, v[118:119], off
	global_load_ushort v215, v[120:121], off
	global_load_ushort v214, v[122:123], off
	s_nop 0
	global_load_ushort v213, v[212:213], off
	s_nop 0
	global_load_ushort v212, v[108:109], off
	s_waitcnt vmcnt(16) lgkmcnt(0)
; __device__ __forceinline__ void unpack8(u32x4 w, float* f) { f[0] = bflo(w.x); f[1] = bfhi(w.x); f[2] = bflo(w.y); f[3] = bfhi(w.y); f[4] = bflo(w.z); f[5] = bfhi(w.z); f[6] = bflo(w.w); f[7] = bfhi(w.w); }
; template <int PASS> __device__ void lru_phase(const Params& p, unsigned char* smem) {
;     ...
;         for (int it = 0; it < 2; ++it) {
;             const int t = (tid >> 4) + 32 * it, c8 = (tid & 15) * 8, ch = jb * 128 + c8;
;             float acc[8];
;             { const f32x4 b0 = *(const f32x4*)(cb + ch), b1 = *(const f32x4*)(cb + ch + 4);
; #pragma unroll
;               for (int i = 0; i < 4; ++i) { acc[i] = b0[i]; acc[4 + i] = b1[i]; } }
; #pragma unroll
;             for (int j = 0; j < 4; ++j) { float xv[8]; unpack8(craw[it][j], xv);
;                 const f32x4 w0 = *(const f32x4*)(cw + j * 2048 + ch), w1 = *(const f32x4*)(cw + j * 2048 + ch + 4);
; #pragma unroll
;                 for (int i = 0; i < 4; ++i) { acc[i] += w0[i] * xv[i]; acc[4 + i] += w1[i] * xv[4 + i]; } }
;             *(f32x4*)(xcf + t * 132 + c8) = (f32x4){acc[0], acc[1], acc[2], acc[3]}; *(f32x4*)(xcf + t * 132 + c8 + 4) = (f32x4){acc[4], acc[5], acc[6], acc[7]};
;         }
;         if (tile + (int)gridDim.x < 4096) LRU_CLOAD(tile + (int)gridDim.x);
	v_lshlrev_b32_e32 v108, 16, v6
	v_and_b32_e32 v109, 0xffff0000, v6
	v_lshlrev_b32_e32 v110, 16, v2
	v_and_b32_e32 v111, 0xffff0000, v2
	v_lshlrev_b32_e32 v112, 16, v4
	v_and_b32_e32 v113, 0xffff0000, v4
	v_lshlrev_b32_e32 v114, 16, v3
	v_and_b32_e32 v115, 0xffff0000, v3
	v_lshlrev_b32_e32 v116, 16, v5
	v_and_b32_e32 v117, 0xffff0000, v5
	s_add_i32 s37, s37, s62
	s_cmpk_gt_i32 s37, 0xfff
	s_cselect_b64 s[22:23], -1, 0
	s_and_b64 vcc, exec, s[22:23]
	v_readlane_b32 s45, v251, 1
	v_readlane_b32 s50, v251, 6
	v_readlane_b32 s51, v251, 7
	v_pk_fma_f32 v[108:109], v[72:73], v[108:109], v[68:69]
	v_readlane_b32 s52, v251, 8
	v_readlane_b32 s53, v251, 9
	v_pk_fma_f32 v[108:109], v[76:77], v[110:111], v[108:109]
	v_lshlrev_b32_e32 v110, 16, v10
	v_and_b32_e32 v111, 0xffff0000, v10
	v_pk_fma_f32 v[108:109], v[80:81], v[110:111], v[108:109]
	v_lshlrev_b32_e32 v110, 16, v14
	v_and_b32_e32 v111, 0xffff0000, v14
	v_pk_fma_f32 v[108:109], v[84:85], v[110:111], v[108:109]
	v_lshlrev_b32_e32 v110, 16, v8
	v_and_b32_e32 v111, 0xffff0000, v8
	v_pk_fma_f32 v[110:111], v[92:93], v[110:111], v[88:89]
	v_readlane_b32 s54, v251, 10
	v_pk_fma_f32 v[110:111], v[96:97], v[112:113], v[110:111]
	v_lshlrev_b32_e32 v112, 16, v12
	v_and_b32_e32 v113, 0xffff0000, v12
	v_pk_fma_f32 v[110:111], v[100:101], v[112:113], v[110:111]
	v_lshlrev_b32_e32 v112, 16, v16
	v_and_b32_e32 v113, 0xffff0000, v16
	v_pk_fma_f32 v[112:113], v[104:105], v[112:113], v[110:111]
	v_lshlrev_b32_e32 v110, 16, v7
	v_and_b32_e32 v111, 0xffff0000, v7
	v_pk_fma_f32 v[110:111], v[74:75], v[110:111], v[70:71]
	v_readlane_b32 s55, v251, 11
	v_pk_fma_f32 v[110:111], v[78:79], v[114:115], v[110:111]
	v_lshlrev_b32_e32 v114, 16, v11
	v_and_b32_e32 v115, 0xffff0000, v11
	v_pk_fma_f32 v[110:111], v[82:83], v[114:115], v[110:111]
	v_lshlrev_b32_e32 v114, 16, v15
	v_and_b32_e32 v115, 0xffff0000, v15
	v_pk_fma_f32 v[110:111], v[86:87], v[114:115], v[110:111]
	v_lshlrev_b32_e32 v114, 16, v9
	v_and_b32_e32 v115, 0xffff0000, v9
	v_pk_fma_f32 v[114:115], v[94:95], v[114:115], v[90:91]
	v_readlane_b32 s56, v251, 12
	v_pk_fma_f32 v[114:115], v[98:99], v[116:117], v[114:115]
	v_lshlrev_b32_e32 v116, 16, v13
	v_and_b32_e32 v117, 0xffff0000, v13
	v_pk_fma_f32 v[114:115], v[102:103], v[116:117], v[114:115]
	v_lshlrev_b32_e32 v116, 16, v17
	v_and_b32_e32 v117, 0xffff0000, v17
	v_pk_fma_f32 v[114:115], v[106:107], v[116:117], v[114:115]
	ds_write_b128 v206, v[108:111]
	ds_write_b128 v206, v[112:115] offset:16
	v_lshlrev_b32_e32 v108, 16, v18
	v_and_b32_e32 v109, 0xffff0000, v18
	v_pk_fma_f32 v[68:69], v[72:73], v[108:109], v[68:69]
	v_lshlrev_b32_e32 v72, 16, v22
	v_and_b32_e32 v73, 0xffff0000, v22
	v_pk_fma_f32 v[68:69], v[76:77], v[72:73], v[68:69]
	v_lshlrev_b32_e32 v72, 16, v26
	v_and_b32_e32 v73, 0xffff0000, v26
	v_pk_fma_f32 v[68:69], v[80:81], v[72:73], v[68:69]
	v_lshlrev_b32_e32 v72, 16, v30
	v_and_b32_e32 v73, 0xffff0000, v30
	v_pk_fma_f32 v[68:69], v[84:85], v[72:73], v[68:69]
	v_lshlrev_b32_e32 v72, 16, v20
	v_and_b32_e32 v73, 0xffff0000, v20
	v_pk_fma_f32 v[72:73], v[92:93], v[72:73], v[88:89]
	v_lshlrev_b32_e32 v76, 16, v24
	v_and_b32_e32 v77, 0xffff0000, v24
	v_pk_fma_f32 v[72:73], v[96:97], v[76:77], v[72:73]
	v_lshlrev_b32_e32 v76, 16, v28
	v_and_b32_e32 v77, 0xffff0000, v28
	v_pk_fma_f32 v[72:73], v[100:101], v[76:77], v[72:73]
	v_lshlrev_b32_e32 v76, 16, v32
	v_and_b32_e32 v77, 0xffff0000, v32
	v_pk_fma_f32 v[72:73], v[104:105], v[76:77], v[72:73]
	v_lshlrev_b32_e32 v76, 16, v19
	v_and_b32_e32 v77, 0xffff0000, v19
	v_pk_fma_f32 v[70:71], v[74:75], v[76:77], v[70:71]
	v_lshlrev_b32_e32 v74, 16, v23
	v_and_b32_e32 v75, 0xffff0000, v23
	v_pk_fma_f32 v[70:71], v[78:79], v[74:75], v[70:71]
	v_lshlrev_b32_e32 v74, 16, v27
	v_and_b32_e32 v75, 0xffff0000, v27
	v_pk_fma_f32 v[70:71], v[82:83], v[74:75], v[70:71]
	v_lshlrev_b32_e32 v74, 16, v31
	v_and_b32_e32 v75, 0xffff0000, v31
	v_pk_fma_f32 v[70:71], v[86:87], v[74:75], v[70:71]
	v_lshlrev_b32_e32 v74, 16, v21
	v_and_b32_e32 v75, 0xffff0000, v21
	v_pk_fma_f32 v[74:75], v[94:95], v[74:75], v[90:91]
	v_lshlrev_b32_e32 v76, 16, v25
	v_and_b32_e32 v77, 0xffff0000, v25
	v_pk_fma_f32 v[74:75], v[98:99], v[76:77], v[74:75]
	v_lshlrev_b32_e32 v76, 16, v29
	v_and_b32_e32 v77, 0xffff0000, v29
	v_pk_fma_f32 v[74:75], v[102:103], v[76:77], v[74:75]
	v_lshlrev_b32_e32 v76, 16, v33
	v_and_b32_e32 v77, 0xffff0000, v33
	v_readlane_b32 s57, v251, 13
	v_readlane_b32 s58, v251, 14
	v_readlane_b32 s59, v251, 15
	v_pk_fma_f32 v[74:75], v[106:107], v[76:77], v[74:75]
	ds_write_b128 v206, v[68:71] offset:16896
	ds_write_b128 v206, v[72:75] offset:16912
	s_cbranch_vccnz .LBB0_552
	s_lshl_b32 s4, s37, 7
	s_and_b32 s4, s4, 0x780
	v_or_b32_e32 v2, s4, v134
	s_and_b32 s63, s37, 0x3f
	s_lshr_b32 s71, s37, 8
	s_lshl_b32 s71, s71, 6
	s_or_b32 s63, s63, s71
	s_bfe_u32 s71, s37, 0x20006
	s_lshl_b32 s71, s71, 10
	s_or_b32 s63, s63, s71
	s_lshl_b32 s4, s63, 2
	s_and_b32 s12, s4, 0xfc0
	v_mov_b32_e32 v4, v67
	v_mov_b32_e32 v5, v67
	v_add_u32_e32 v14, s12, v135
	v_lshlrev_b32_e32 v66, 1, v2
	v_mov_b32_e32 v2, v67
	v_mov_b32_e32 v3, v67
	v_mov_b64_e32 v[8:9], v[4:5]
	s_and_b32 s41, s4, 0xfffff000
	v_lshl_add_u64 v[30:31], s[0:1], 0, v[66:67]
	v_cmp_lt_i32_e32 vcc, -1, v14
	v_mov_b64_e32 v[6:7], v[2:3]
	s_and_saveexec_b64 s[4:5], vcc
	s_cbranch_execz .LBB0_545
	v_add_u32_e32 v6, s41, v14
	v_ashrrev_i32_e32 v7, 31, v6
	v_lshlrev_b64 v[6:7], 12, v[6:7]
	v_lshl_add_u64 v[6:7], v[30:31], 0, v[6:7]
	global_load_dwordx4 v[6:9], v[6:7], off

; __device__ __forceinline__ float softplusf_(float x) { return fmaxf(x, 0.f) + log1pf(__expf(-fabsf(x))); }
; __device__ __forceinline__ float fsig0(float x) { return __builtin_amdgcn_rcpf(1.0f + __expf(-x)); }
; template <int PASS> __device__ void lru_phase(const Params& p, unsigned char* smem) {
;     ...
;         {
;             const int ch = 16 * wave + (lane & 15), cgl = jb * 128 + ch;
;             const float ba_ = jb_fixed ? hb_a : p.in[6][cgl], bx_ = jb_fixed ? hb_x : p.in[8][cgl], sp = jb_fixed ? hsp : softplusf_(-p.in[9][cgl]);
; #pragma unroll
;             for (int m = 0; m < 4; ++m)
; #pragma unroll
;                 for (int r = 0; r < 4; ++r) { const int t = 16 * m + 4 * (lane >> 4) + r;
;                     const float rg = fsig0(accA[m][r] + ba_), ig = fsig0(accX[m][r] + bx_);
;                     const float la = -8.0f * rg * sp, a = __expf(la), u = __builtin_amdgcn_sqrtf(fmaxf(1.0f - a * a, 0.f)) * (ig * xcf[t * 132 + ch]);
;                     As[t * 132 + ch] = a; Us[t * 132 + ch] = u; }
.LBB0_572:
	s_waitcnt vmcnt(0)
	v_add_f32_e32 v66, v96, v100
	v_add_f32_e32 v96, v97, v100
	v_mul_f32_e32 v96, 0xbfb8aa3b, v96
	v_exp_f32_e32 v96, v96
	v_mul_f32_e32 v66, 0xbfb8aa3b, v66
	v_exp_f32_e32 v66, v66
	v_add_f32_e32 v93, v93, v101
	v_add_f32_e32 v96, 1.0, v96
	v_rcp_f32_e32 v96, v96
	v_add_f32_e32 v66, 1.0, v66
	v_mul_f32_e32 v93, 0xbfb8aa3b, v93
	v_rcp_f32_e32 v66, v66
	v_mul_f32_e32 v96, 0xc1000000, v96
	v_mul_f32_e32 v96, v96, v102
	v_mul_f32_e32 v96, 0x3fb8aa3b, v96
	v_exp_f32_e32 v93, v93
	v_exp_f32_e32 v96, v96
	ds_read2_b32 v[104:105], v141 offset1:132
	v_mul_f32_e32 v66, 0xc1000000, v66
	v_add_f32_e32 v93, 1.0, v93
	v_fma_f32 v103, -v96, v96, 1.0
	v_mul_f32_e32 v66, v66, v102
	v_rcp_f32_e32 v93, v93
	v_max_f32_e32 v103, 0, v103
	v_add_f32_e32 v98, v98, v100
	v_mul_f32_e32 v66, 0x3fb8aa3b, v66
	v_sqrt_f32_e32 v103, v103
	v_mul_f32_e32 v98, 0xbfb8aa3b, v98
	v_exp_f32_e32 v66, v66
	v_exp_f32_e32 v98, v98
	s_waitcnt lgkmcnt(0)
	v_mul_f32_e32 v93, v93, v105
	v_mul_f32_e32 v93, v93, v103
	v_add_u32_e32 v103, 0x8400, v141
	v_fma_f32 v97, -v66, v66, 1.0
	ds_write2_b32 v103, v66, v96 offset1:132
	v_add_f32_e32 v66, 1.0, v98
	v_rcp_f32_e32 v66, v66
	v_add_f32_e32 v94, v94, v101
	v_add_f32_e32 v98, v99, v100
	v_mul_f32_e32 v94, 0xbfb8aa3b, v94
	v_mul_f32_e32 v66, 0xc1000000, v66
	v_mul_f32_e32 v66, v66, v102
	v_mul_f32_e32 v66, 0x3fb8aa3b, v66
	v_mul_f32_e32 v98, 0xbfb8aa3b, v98
	v_exp_f32_e32 v94, v94
	v_exp_f32_e32 v66, v66
	v_exp_f32_e32 v98, v98
	ds_write_b32 v143, v93
	v_add_f32_e32 v93, 1.0, v94
	v_fma_f32 v94, -v66, v66, 1.0
	ds_read_b32 v96, v141 offset:1056
	ds_write_b32 v141, v66 offset:34848
	v_add_f32_e32 v66, 1.0, v98
	v_rcp_f32_e32 v93, v93
	v_max_f32_e32 v94, 0, v94
	v_rcp_f32_e32 v66, v66
	v_sqrt_f32_e32 v94, v94
	s_waitcnt lgkmcnt(1)
	v_mul_f32_e32 v93, v93, v96
	v_add_f32_e32 v88, v88, v100
	v_mul_f32_e32 v66, 0xc1000000, v66
	v_mul_f32_e32 v93, v94, v93
	v_add_f32_e32 v94, v95, v101
	v_mul_f32_e32 v66, v66, v102
	v_mul_f32_e32 v94, 0xbfb8aa3b, v94
	v_mul_f32_e32 v66, 0x3fb8aa3b, v66
	v_mul_f32_e32 v88, 0xbfb8aa3b, v88
	v_exp_f32_e32 v94, v94
	v_exp_f32_e32 v66, v66
	v_exp_f32_e32 v88, v88
	ds_write_b32 v144, v93
	v_add_f32_e32 v93, 1.0, v94
	v_fma_f32 v94, -v66, v66, 1.0
	ds_write_b32 v141, v66 offset:35376
	v_add_f32_e32 v66, 1.0, v88
	v_rcp_f32_e32 v66, v66
	ds_read_b32 v95, v141 offset:1584
	v_rcp_f32_e32 v93, v93
	v_max_f32_e32 v94, 0, v94
	v_mul_f32_e32 v66, 0xc1000000, v66
	v_mul_f32_e32 v66, v66, v102
	v_add_f32_e32 v89, v89, v100
	v_sqrt_f32_e32 v94, v94
	v_mul_f32_e32 v66, 0x3fb8aa3b, v66
	v_mul_f32_e32 v89, 0xbfb8aa3b, v89
	v_exp_f32_e32 v66, v66
	v_exp_f32_e32 v89, v89
	s_waitcnt lgkmcnt(0)
	v_mul_f32_e32 v93, v93, v95
	v_add_f32_e32 v84, v84, v101
	v_mul_f32_e32 v93, v94, v93
	v_mul_f32_e32 v84, 0xbfb8aa3b, v84
	v_exp_f32_e32 v84, v84
	ds_write_b32 v145, v93
	v_fma_f32 v88, -v66, v66, 1.0
	ds_write_b32 v141, v66 offset:42240
	v_add_f32_e32 v66, 1.0, v89
	v_rcp_f32_e32 v66, v66
	v_add_f32_e32 v84, 1.0, v84
	ds_read_b32 v93, v141 offset:8448
	v_rcp_f32_e32 v84, v84
	v_max_f32_e32 v88, 0, v88
	v_mul_f32_e32 v66, 0xc1000000, v66
	v_sqrt_f32_e32 v88, v88
	v_add_f32_e32 v85, v85, v101
	v_mul_f32_e32 v66, v66, v102
	v_add_f32_e32 v89, v90, v100
	v_mul_f32_e32 v85, 0xbfb8aa3b, v85
	v_mul_f32_e32 v66, 0x3fb8aa3b, v66
	v_mul_f32_e32 v89, 0xbfb8aa3b, v89
	v_exp_f32_e32 v85, v85
	v_exp_f32_e32 v66, v66
	v_exp_f32_e32 v89, v89
	s_waitcnt lgkmcnt(0)
	v_mul_f32_e32 v84, v84, v93
	v_mul_f32_e32 v84, v88, v84
	ds_write_b32 v146, v84
	v_add_f32_e32 v84, 1.0, v85
	v_fma_f32 v85, -v66, v66, 1.0
	ds_read_b32 v88, v141 offset:8976
	ds_write_b32 v141, v66 offset:42768
	v_add_f32_e32 v66, 1.0, v89
	v_rcp_f32_e32 v84, v84
	v_max_f32_e32 v85, 0, v85
	v_rcp_f32_e32 v66, v66
	v_sqrt_f32_e32 v85, v85
	s_waitcnt lgkmcnt(1)
	v_mul_f32_e32 v84, v84, v88
	v_add_f32_e32 v88, v91, v100
	v_mul_f32_e32 v66, 0xc1000000, v66
	v_mul_f32_e32 v84, v85, v84
	v_add_f32_e32 v85, v86, v101
	v_mul_f32_e32 v66, v66, v102
	v_mul_f32_e32 v85, 0xbfb8aa3b, v85
	v_mul_f32_e32 v66, 0x3fb8aa3b, v66
	v_mul_f32_e32 v88, 0xbfb8aa3b, v88
	v_exp_f32_e32 v85, v85
	v_exp_f32_e32 v66, v66
	v_exp_f32_e32 v88, v88
	ds_write_b32 v147, v84
	v_add_f32_e32 v84, 1.0, v85
	v_fma_f32 v85, -v66, v66, 1.0
	ds_read_b32 v86, v141 offset:9504
	ds_write_b32 v141, v66 offset:43296
	v_add_f32_e32 v66, 1.0, v88
	v_rcp_f32_e32 v84, v84
	v_max_f32_e32 v85, 0, v85
	v_rcp_f32_e32 v66, v66
	v_sqrt_f32_e32 v85, v85
	s_waitcnt lgkmcnt(1)
	v_mul_f32_e32 v84, v84, v86
	v_add_f32_e32 v80, v80, v100
	v_mul_f32_e32 v66, 0xc1000000, v66
	v_mul_f32_e32 v84, v85, v84
	v_add_f32_e32 v85, v87, v101
	v_mul_f32_e32 v66, v66, v102
	v_mul_f32_e32 v85, 0xbfb8aa3b, v85
	v_mul_f32_e32 v66, 0x3fb8aa3b, v66
	v_mul_f32_e32 v80, 0xbfb8aa3b, v80
	v_exp_f32_e32 v85, v85
	v_exp_f32_e32 v66, v66
	v_exp_f32_e32 v80, v80
	ds_write_b32 v148, v84
	v_add_f32_e32 v84, 1.0, v85
	v_fma_f32 v85, -v66, v66, 1.0
	ds_write_b32 v141, v66 offset:43824
	v_add_f32_e32 v66, 1.0, v80
	v_rcp_f32_e32 v66, v66
	ds_read_b32 v86, v141 offset:10032
	v_rcp_f32_e32 v84, v84
	v_max_f32_e32 v85, 0, v85
	v_mul_f32_e32 v66, 0xc1000000, v66
	v_mul_f32_e32 v66, v66, v102
	v_add_f32_e32 v81, v81, v100
	v_sqrt_f32_e32 v85, v85
	v_mul_f32_e32 v66, 0x3fb8aa3b, v66
	v_mul_f32_e32 v81, 0xbfb8aa3b, v81
	v_exp_f32_e32 v66, v66
	v_exp_f32_e32 v81, v81
	s_waitcnt lgkmcnt(0)
; __device__ __forceinline__ float softplusf_(float x) { return fmaxf(x, 0.f) + log1pf(__expf(-fabsf(x))); }
; #define LBAR0() do { asm volatile("s_waitcnt lgkmcnt(0)" ::: "memory"); __builtin_amdgcn_s_barrier(); asm volatile("" ::: "memory"); } while (0)
; __device__ __forceinline__ float fsig0(float x) { return __builtin_amdgcn_rcpf(1.0f + __expf(-x)); }
; template <int PASS> __device__ void lru_phase(const Params& p, unsigned char* smem) {
;     ...
;         {
;             const int ch = 16 * wave + (lane & 15), cgl = jb * 128 + ch;
;             const float ba_ = jb_fixed ? hb_a : p.in[6][cgl], bx_ = jb_fixed ? hb_x : p.in[8][cgl], sp = jb_fixed ? hsp : softplusf_(-p.in[9][cgl]);
; #pragma unroll
;             for (int m = 0; m < 4; ++m)
; #pragma unroll
;                 for (int r = 0; r < 4; ++r) { const int t = 16 * m + 4 * (lane >> 4) + r;
;                     const float rg = fsig0(accA[m][r] + ba_), ig = fsig0(accX[m][r] + bx_);
;                     const float la = -8.0f * rg * sp, a = __expf(la), u = __builtin_amdgcn_sqrtf(fmaxf(1.0f - a * a, 0.f)) * (ig * xcf[t * 132 + ch]);
;                     As[t * 132 + ch] = a; Us[t * 132 + ch] = u; }
;         }
;         LBAR0();
	v_mul_f32_e32 v84, v84, v86
	v_add_f32_e32 v76, v76, v101
	v_mul_f32_e32 v84, v85, v84
	v_mul_f32_e32 v76, 0xbfb8aa3b, v76
	v_exp_f32_e32 v76, v76
	ds_write_b32 v149, v84
	v_fma_f32 v80, -v66, v66, 1.0
	ds_write_b32 v141, v66 offset:50688
	v_add_f32_e32 v66, 1.0, v81
	v_rcp_f32_e32 v66, v66
	v_add_f32_e32 v76, 1.0, v76
	ds_read_b32 v84, v141 offset:16896
	v_rcp_f32_e32 v76, v76
	v_max_f32_e32 v80, 0, v80
	v_mul_f32_e32 v66, 0xc1000000, v66
	v_sqrt_f32_e32 v80, v80
	v_add_f32_e32 v77, v77, v101
	v_mul_f32_e32 v66, v66, v102
	v_add_f32_e32 v81, v82, v100
	v_mul_f32_e32 v77, 0xbfb8aa3b, v77
	v_mul_f32_e32 v66, 0x3fb8aa3b, v66
	v_mul_f32_e32 v81, 0xbfb8aa3b, v81
	v_exp_f32_e32 v77, v77
	v_exp_f32_e32 v66, v66
	v_exp_f32_e32 v81, v81
	s_waitcnt lgkmcnt(0)
	v_mul_f32_e32 v76, v76, v84
	v_mul_f32_e32 v76, v80, v76
	ds_write_b32 v150, v76
	v_add_f32_e32 v76, 1.0, v77
	v_fma_f32 v77, -v66, v66, 1.0
	ds_read_b32 v80, v141 offset:17424
	ds_write_b32 v141, v66 offset:51216
	v_add_f32_e32 v66, 1.0, v81
	v_rcp_f32_e32 v76, v76
	v_max_f32_e32 v77, 0, v77
	v_rcp_f32_e32 v66, v66
	v_sqrt_f32_e32 v77, v77
	s_waitcnt lgkmcnt(1)
	v_mul_f32_e32 v76, v76, v80
	v_add_f32_e32 v80, v83, v100
	v_mul_f32_e32 v66, 0xc1000000, v66
	v_mul_f32_e32 v76, v77, v76
	v_add_f32_e32 v77, v78, v101
	v_mul_f32_e32 v66, v66, v102
	v_mul_f32_e32 v77, 0xbfb8aa3b, v77
	v_mul_f32_e32 v66, 0x3fb8aa3b, v66
	v_mul_f32_e32 v80, 0xbfb8aa3b, v80
	v_exp_f32_e32 v77, v77
	v_exp_f32_e32 v66, v66
	v_exp_f32_e32 v80, v80
	ds_write_b32 v151, v76
	v_add_f32_e32 v76, 1.0, v77
	v_fma_f32 v77, -v66, v66, 1.0
	ds_read_b32 v78, v141 offset:17952
	ds_write_b32 v141, v66 offset:51744
	v_add_f32_e32 v66, 1.0, v80
	v_rcp_f32_e32 v76, v76
	v_max_f32_e32 v77, 0, v77
	v_rcp_f32_e32 v66, v66
	v_sqrt_f32_e32 v77, v77
	s_waitcnt lgkmcnt(1)
	v_mul_f32_e32 v76, v76, v78
	v_add_f32_e32 v72, v72, v100
	v_mul_f32_e32 v66, 0xc1000000, v66
	v_mul_f32_e32 v76, v77, v76
	v_add_f32_e32 v77, v79, v101
	v_mul_f32_e32 v66, v66, v102
	v_mul_f32_e32 v77, 0xbfb8aa3b, v77
	v_mul_f32_e32 v66, 0x3fb8aa3b, v66
	v_mul_f32_e32 v72, 0xbfb8aa3b, v72
	v_exp_f32_e32 v77, v77
	v_exp_f32_e32 v66, v66
	v_exp_f32_e32 v72, v72
	ds_write_b32 v152, v76
	v_add_f32_e32 v76, 1.0, v77
	v_fma_f32 v77, -v66, v66, 1.0
	ds_write_b32 v141, v66 offset:52272
	v_add_f32_e32 v66, 1.0, v72
	v_rcp_f32_e32 v66, v66
	ds_read_b32 v78, v141 offset:18480
	v_rcp_f32_e32 v76, v76
	v_max_f32_e32 v77, 0, v77
	v_mul_f32_e32 v66, 0xc1000000, v66
	v_mul_f32_e32 v66, v66, v102
	v_add_f32_e32 v73, v73, v100
	v_sqrt_f32_e32 v77, v77
	v_mul_f32_e32 v66, 0x3fb8aa3b, v66
	v_mul_f32_e32 v73, 0xbfb8aa3b, v73
	v_exp_f32_e32 v66, v66
	v_exp_f32_e32 v73, v73
	s_waitcnt lgkmcnt(0)
	v_mul_f32_e32 v76, v76, v78
	v_add_f32_e32 v68, v68, v101
	v_mul_f32_e32 v76, v77, v76
	v_mul_f32_e32 v68, 0xbfb8aa3b, v68
	v_exp_f32_e32 v68, v68
	ds_write_b32 v153, v76
	v_fma_f32 v72, -v66, v66, 1.0
	ds_write_b32 v141, v66 offset:59136
	v_add_f32_e32 v66, 1.0, v73
	v_rcp_f32_e32 v66, v66
	v_add_f32_e32 v68, 1.0, v68
	ds_read_b32 v76, v141 offset:25344
	v_rcp_f32_e32 v68, v68
	v_max_f32_e32 v72, 0, v72
	v_mul_f32_e32 v66, 0xc1000000, v66
	v_sqrt_f32_e32 v72, v72
	v_add_f32_e32 v69, v69, v101
	v_mul_f32_e32 v66, v66, v102
	v_add_f32_e32 v73, v74, v100
	v_mul_f32_e32 v69, 0xbfb8aa3b, v69
	v_mul_f32_e32 v66, 0x3fb8aa3b, v66
	v_mul_f32_e32 v73, 0xbfb8aa3b, v73
	v_exp_f32_e32 v69, v69
	v_exp_f32_e32 v66, v66
	v_exp_f32_e32 v73, v73
	s_waitcnt lgkmcnt(0)
	v_mul_f32_e32 v68, v68, v76
	v_mul_f32_e32 v68, v72, v68
	ds_write_b32 v154, v68
	v_add_f32_e32 v68, 1.0, v69
	v_fma_f32 v69, -v66, v66, 1.0
	ds_read_b32 v72, v141 offset:25872
	ds_write_b32 v141, v66 offset:59664
	v_add_f32_e32 v66, 1.0, v73
	v_rcp_f32_e32 v68, v68
	v_max_f32_e32 v69, 0, v69
	v_rcp_f32_e32 v66, v66
	v_sqrt_f32_e32 v69, v69
	s_waitcnt lgkmcnt(1)
	v_mul_f32_e32 v68, v68, v72
	v_add_f32_e32 v72, v75, v100
	v_mul_f32_e32 v66, 0xc1000000, v66
	v_mul_f32_e32 v68, v69, v68
	v_add_f32_e32 v69, v70, v101
	v_mul_f32_e32 v66, v66, v102
	v_mul_f32_e32 v69, 0xbfb8aa3b, v69
	v_mul_f32_e32 v66, 0x3fb8aa3b, v66
	v_mul_f32_e32 v72, 0xbfb8aa3b, v72
	v_exp_f32_e32 v69, v69
	v_exp_f32_e32 v66, v66
	v_exp_f32_e32 v72, v72
	ds_write_b32 v155, v68
	v_add_f32_e32 v68, 1.0, v69
	v_fma_f32 v69, -v66, v66, 1.0
	ds_read_b32 v70, v141 offset:26400
	ds_write_b32 v141, v66 offset:60192
	v_add_f32_e32 v66, 1.0, v72
	v_rcp_f32_e32 v68, v68
	v_max_f32_e32 v69, 0, v69
	v_rcp_f32_e32 v66, v66
	v_sqrt_f32_e32 v69, v69
	v_add_f32_e32 v92, v92, v101
	s_waitcnt lgkmcnt(1)
	v_mul_f32_e32 v68, v68, v70
	v_mul_f32_e32 v66, 0xc1000000, v66
	v_mul_f32_e32 v92, 0xbfb8aa3b, v92
	v_mul_f32_e32 v68, v69, v68
	v_add_f32_e32 v69, v71, v101
	v_mul_f32_e32 v66, v66, v102
	v_exp_f32_e32 v92, v92
	v_mul_f32_e32 v69, 0xbfb8aa3b, v69
	v_mul_f32_e32 v66, 0x3fb8aa3b, v66
	v_exp_f32_e32 v69, v69
	v_exp_f32_e32 v66, v66
	v_add_f32_e32 v92, 1.0, v92
	ds_write_b32 v156, v68
	v_rcp_f32_e32 v92, v92
	v_max_f32_e32 v97, 0, v97
	v_add_f32_e32 v68, 1.0, v69
	v_fma_f32 v69, -v66, v66, 1.0
	ds_read_b32 v70, v141 offset:26928
	v_sqrt_f32_e32 v97, v97
	v_rcp_f32_e32 v68, v68
	v_max_f32_e32 v69, 0, v69
	v_sqrt_f32_e32 v69, v69
	v_mul_f32_e32 v92, v92, v104
	v_mul_f32_e32 v71, v92, v97
	s_waitcnt lgkmcnt(0)
	v_mul_f32_e32 v68, v68, v70
	ds_write_b32 v142, v71
	v_mul_f32_e32 v68, v69, v68
	ds_write_b32 v141, v66 offset:60720
	ds_write_b32 v157, v68
	s_waitcnt lgkmcnt(0)
	s_barrier
; #define LBAR0() do { asm volatile("s_waitcnt lgkmcnt(0)" ::: "memory"); __builtin_amdgcn_s_barrier(); asm volatile("" ::: "memory"); } while (0)
; template <int PASS> __device__ void lru_phase(const Params& p, unsigned char* smem) {
;     ...
;         { float h = 0.f, A = 1.f;
; #pragma unroll
;           for (int tt = 0; tt < 16; ++tt) { const int t = q * 16 + tt; const float a = As[t * 132 + ch], u = Us[t * 132 + ch]; h = a * h + u; A *= a;
;               if (PASS == 2) { Us[t * 132 + ch] = h; As[t * 132 + ch] = A; } }
;           qA[q * 128 + ch] = A; qH[q * 128 + ch] = h; }
;         LBAR0();
;         if (PASS == 1) {
;             if (q == 0) { float h = 0.f, A = 1.f;
; #pragma unroll
;                 for (int qq = 0; qq < 4; ++qq) { h = qA[qq * 128 + ch] * h + qH[qq * 128 + ch]; A *= qA[qq * 128 + ch]; }
;                 LA[(size_t)(b * 64 + c) * 2048 + cgl] = A; LH[(size_t)(b * 64 + c) * 2048 + cgl] = h; }
	ds_read_b32 v66, v158 offset:33792
	ds_read_b32 v68, v1
	s_lshl_b32 s4, s25, 6
	s_or_b32 s4, s4, s24
	s_ashr_i32 s5, s4, 31
	s_lshl_b64 s[4:5], s[4:5], 13
	s_waitcnt lgkmcnt(0)
	v_fmac_f32_e32 v68, 0, v66
	ds_write_b32 v1, v68
	ds_read_b32 v69, v160 offset:33792
	ds_read_b32 v70, v161
	s_add_u32 s4, s26, s4
	s_addc_u32 s5, s27, s5
	s_waitcnt lgkmcnt(1)
	v_mul_f32_e32 v66, v66, v69
	s_waitcnt lgkmcnt(0)
	v_fmac_f32_e32 v70, v68, v69
	ds_write_b32 v161, v70
	ds_write_b32 v160, v66 offset:33792
	ds_read_b32 v68, v163 offset:33792
	ds_read_b32 v69, v164
	s_waitcnt lgkmcnt(1)
	v_mul_f32_e32 v66, v66, v68
	s_waitcnt lgkmcnt(0)
	v_fmac_f32_e32 v69, v70, v68
	ds_write_b32 v164, v69
	ds_write_b32 v163, v66 offset:33792
	ds_read_b32 v68, v166 offset:33792
	ds_read_b32 v70, v167
	s_waitcnt lgkmcnt(1)
	v_mul_f32_e32 v66, v66, v68
	s_waitcnt lgkmcnt(0)
	v_fmac_f32_e32 v70, v69, v68
	ds_write_b32 v167, v70
	ds_write_b32 v166, v66 offset:33792
	ds_read_b32 v68, v169 offset:33792
	ds_read_b32 v69, v170
	s_waitcnt lgkmcnt(1)
	v_mul_f32_e32 v66, v66, v68
	s_waitcnt lgkmcnt(0)
	v_fmac_f32_e32 v69, v70, v68
	ds_write_b32 v170, v69
	ds_write_b32 v169, v66 offset:33792
	ds_read_b32 v68, v172 offset:33792
	ds_read_b32 v70, v173
	s_waitcnt lgkmcnt(1)
	v_mul_f32_e32 v66, v66, v68
	s_waitcnt lgkmcnt(0)
	v_fmac_f32_e32 v70, v69, v68
	ds_write_b32 v173, v70
	ds_write_b32 v172, v66 offset:33792
	ds_read_b32 v68, v175 offset:33792
	ds_read_b32 v69, v176
	s_waitcnt lgkmcnt(1)
	v_mul_f32_e32 v66, v66, v68
	s_waitcnt lgkmcnt(0)
	v_fmac_f32_e32 v69, v70, v68
	ds_write_b32 v176, v69
	ds_write_b32 v175, v66 offset:33792
	ds_read_b32 v68, v178 offset:33792
	ds_read_b32 v70, v179
	s_waitcnt lgkmcnt(1)
	v_mul_f32_e32 v66, v66, v68
	s_waitcnt lgkmcnt(0)
	v_fmac_f32_e32 v70, v69, v68
	ds_write_b32 v179, v70
	ds_write_b32 v178, v66 offset:33792
	ds_read_b32 v68, v181 offset:33792
	ds_read_b32 v69, v182
	s_waitcnt lgkmcnt(1)
	v_mul_f32_e32 v66, v66, v68
	s_waitcnt lgkmcnt(0)
	v_fmac_f32_e32 v69, v70, v68
	ds_write_b32 v182, v69
	ds_write_b32 v181, v66 offset:33792
	ds_read_b32 v68, v184 offset:33792
	ds_read_b32 v70, v185
	s_waitcnt lgkmcnt(1)
	v_mul_f32_e32 v66, v66, v68
	s_waitcnt lgkmcnt(0)
	v_fmac_f32_e32 v70, v69, v68
	ds_write_b32 v185, v70
	ds_write_b32 v184, v66 offset:33792
	ds_read_b32 v68, v187 offset:33792
	ds_read_b32 v69, v188
	s_waitcnt lgkmcnt(1)
	v_mul_f32_e32 v66, v66, v68
	s_waitcnt lgkmcnt(0)
	v_fmac_f32_e32 v69, v70, v68
	ds_write_b32 v188, v69
	ds_write_b32 v187, v66 offset:33792
	ds_read_b32 v68, v190 offset:33792
	ds_read_b32 v70, v191
	s_waitcnt lgkmcnt(1)
	v_mul_f32_e32 v66, v66, v68
	s_waitcnt lgkmcnt(0)
	v_fmac_f32_e32 v70, v69, v68
	ds_write_b32 v191, v70
	ds_write_b32 v190, v66 offset:33792
	ds_read_b32 v68, v193 offset:33792
	ds_read_b32 v69, v194
	s_waitcnt lgkmcnt(1)
	v_mul_f32_e32 v66, v66, v68
	s_waitcnt lgkmcnt(0)
	v_fmac_f32_e32 v69, v70, v68
	ds_write_b32 v194, v69
	ds_write_b32 v193, v66 offset:33792
	ds_read_b32 v68, v196 offset:33792
	ds_read_b32 v70, v197
	s_waitcnt lgkmcnt(1)
	v_mul_f32_e32 v66, v66, v68
	s_waitcnt lgkmcnt(0)
	v_fmac_f32_e32 v70, v69, v68
	ds_write_b32 v197, v70
	ds_write_b32 v196, v66 offset:33792
	ds_read_b32 v68, v199 offset:33792
	ds_read_b32 v69, v200
	s_waitcnt lgkmcnt(1)
	v_mul_f32_e32 v66, v66, v68
	s_waitcnt lgkmcnt(0)
	v_fmac_f32_e32 v69, v70, v68
	ds_write_b32 v200, v69
	ds_write_b32 v199, v66 offset:33792
	ds_read_b32 v68, v202 offset:33792
	ds_read_b32 v70, v203
	s_waitcnt lgkmcnt(0)
	v_fmac_f32_e32 v70, v69, v68
	v_mul_f32_e32 v68, v66, v68
	ds_write_b32 v203, v70
	ds_write_b32 v202, v68 offset:33792
	v_or_b32_e32 v66, s39, v132
	ds_write_b32 v139, v68
	ds_write_b32 v140, v70
	s_waitcnt lgkmcnt(0)
	s_barrier
	v_lshlrev_b32_e32 v68, 2, v66
	v_bfe_u32 v85, v0, 6, 3
	s_sub_i32 s40, s37, s62
	s_and_b32 s63, s40, 0x3f
	s_lshr_b32 s71, s40, 8
	s_lshl_b32 s71, s71, 6
	s_or_b32 s63, s63, s71
	s_bfe_u32 s71, s40, 0x20006
	s_lshl_b32 s71, s71, 10
	s_or_b32 s63, s63, s71
	s_bfe_u32 s41, s63, 0x60004
	s_lshr_b32 s42, s63, 10
	s_nop 0
	v_readfirstlane_b32 s47, v85
	s_lshl_b32 s44, s42, 6
	s_or_b32 s44, s44, s41
	s_cmp_lt_u32 s47, 2
	s_cbranch_scc0 LRUX_join
	s_add_u32 s48, s64, 0x1f100000
	s_addc_u32 s49, s65, 0
	v_add_u32_e32 v71, 0xfffff800, v205
	ds_read_b32 v72, v71
	ds_read_b32 v73, v71 offset:512
	ds_read_b32 v74, v71 offset:1024
	ds_read_b32 v75, v71 offset:1536
	ds_read_b32 v76, v71 offset:2048
	ds_read_b32 v77, v71 offset:2560
	ds_read_b32 v78, v71 offset:3072
	ds_read_b32 v79, v71 offset:3584
	s_lshl_b32 s45, s44, 14
	v_lshl_add_u32 v82, v66, 3, s45
	s_waitcnt lgkmcnt(0)
	v_fma_f32 v81, v73, v76, v77
	v_mul_f32_e32 v80, v72, v73
	v_fma_f32 v81, v74, v81, v78
	v_mul_f32_e32 v80, v80, v74
	v_fma_f32 v81, v75, v81, v79
	v_mul_f32_e32 v80, v80, v75
	global_store_dwordx2 v82, v[80:81], s[48:49] sc0 sc1
	s_cmp_lt_u32 s41, 4
	s_cbranch_scc0 LRUX_keepP
	v_mov_b32_e32 v252, 0

; template <int PASS> __device__ void lru_phase(const Params& p, unsigned char* smem) {
;     ...
;             float carry = LC[(size_t)(b * 64 + c) * 2048 + cgl];
;             for (int qq = 0; qq < q; ++qq) carry = qA[qq * 128 + ch] * carry + qH[qq * 128 + ch];
LRUX_ld3:
	s_waitcnt vmcnt(0)
	s_cmp_lt_u32 s41, 1
	s_cbranch_scc1 LRUX_mx1
	v_max_u32_e32 v86, v86, v98

; template <int PASS> __device__ void lru_phase(const Params& p, unsigned char* smem) {
;     ...
;             float carry = LC[(size_t)(b * 64 + c) * 2048 + cgl];
;             for (int qq = 0; qq < q; ++qq) carry = qA[qq * 128 + ch] * carry + qH[qq * 128 + ch];
LRUX_mx3:
	v_cmp_eq_u32_e32 vcc, -1, v86
	s_cbranch_vccz LRUX_polled
	s_add_i32 s59, s59, -1
	s_cmp_eq_u32 s59, 0
	s_cbranch_scc1 LRUX_polled
	s_sleep 1
	s_branch LRUX_poll
LRUX_polled:
	v_mov_b32_e32 v70, v252
	s_cmp_lt_u32 s41, 3
	s_cbranch_scc1 LRUX_sk3
	v_fma_f32 v70, v102, v70, v103
